# hyena epilogue: the 8 gate loads per 128-row group issued together with counted waits
# speedup vs baseline: 1.0577x; 1.0018x over previous
; __device__ __forceinline__ unsigned cvt_pk_bf16(float lo, float hi) { const f32x2_t v = {lo, hi}; const bf16x2_t b = __builtin_convertvector(v, bf16x2_t); return __builtin_bit_cast(unsigned, b); }
; __device__ __forceinline__ float lo_bf(unsigned w) { return __uint_as_float(w << 16); }
; __device__ __forceinline__ float hi_bf(unsigned w) { return __uint_as_float(w & 0xffff0000u); }
; __device__ void hyena_phase(unsigned char* smem, const Params& p, int l, int order) {
;     ...
;             for (int mi = 0; mi < 8; ++mi) { const int t = tb + mi * 16 + 4 * g4;
;                 const u32x2 gw = *(const u32x2*)(gin + (size_t)r16 * SEQ + t); const u32x2 zw = *(const u32x2*)(zs + r16 * ZS + t);
;                 const float gv[4] = {lo_bf(gw.x), hi_bf(gw.x), lo_bf(gw.y), hi_bf(gw.y)}; const float zv[4] = {lo_bf(zw.x), hi_bf(zw.x), lo_bf(zw.y), hi_bf(zw.y)};
;                 float o[4];
; #pragma unroll
;                 for (int i = 0; i < 4; ++i) o[i] = gv[i] * (acc[mi][i] + sk * zv[i]);
;                 u32x2 wv; wv.x = cvt_pk_bf16(o[0], o[1]); wv.y = cvt_pk_bf16(o[2], o[3]); *(u32x2*)(dst + (size_t)r16 * SEQ + t) = wv; }
.LBB0_198:
	v_lshl_add_u64 v[2:3], v[104:105], 0, v[98:99]
	global_load_dwordx2 v[158:159], v[2:3], off offset:256
	global_load_dwordx2 v[160:161], v[2:3], off offset:288
	global_load_dwordx2 v[162:163], v[2:3], off offset:320
	global_load_dwordx2 v[164:165], v[2:3], off offset:352
	global_load_dwordx2 v[166:167], v[2:3], off offset:384
	global_load_dwordx2 v[168:169], v[2:3], off offset:416
	global_load_dwordx2 v[170:171], v[2:3], off offset:448
	global_load_dwordx2 v[172:173], v[2:3], off offset:480
	ds_read2_b64 v[24:27], v127 offset0:32 offset1:36
	v_lshl_add_u64 v[0:1], v[102:103], 0, v[98:99]
	v_readlane_b32 s0, v254, 19
	v_readlane_b32 s1, v254, 20
	s_waitcnt lgkmcnt(0)
	v_lshlrev_b32_e32 v30, 16, v24
	v_and_b32_e32 v31, 0xffff0000, v24
	v_lshlrev_b32_e32 v24, 16, v25
	v_and_b32_e32 v25, 0xffff0000, v25
	v_pk_fma_f32 v[30:31], v[100:101], v[30:31], v[64:65]
	v_pk_fma_f32 v[24:25], v[100:101], v[24:25], v[66:67]
	s_waitcnt vmcnt(7)
	v_lshlrev_b32_e32 v36, 16, v158
	v_and_b32_e32 v37, 0xffff0000, v158
	v_lshlrev_b32_e32 v28, 16, v159
	v_and_b32_e32 v29, 0xffff0000, v159
	v_pk_mul_f32 v[30:31], v[30:31], v[36:37]
	v_pk_mul_f32 v[24:25], v[24:25], v[28:29]
	v_cvt_pk_bf16_f32 v28, v30, v31
	v_cvt_pk_bf16_f32 v29, v24, v25
	global_store_dwordx2 v[0:1], v[28:29], off offset:256
	v_lshlrev_b32_e32 v28, 16, v26
	v_and_b32_e32 v29, 0xffff0000, v26
	v_lshlrev_b32_e32 v26, 16, v27
	v_and_b32_e32 v27, 0xffff0000, v27
	v_pk_fma_f32 v[28:29], v[100:101], v[28:29], v[52:53]
	v_pk_fma_f32 v[26:27], v[100:101], v[26:27], v[54:55]
	s_waitcnt vmcnt(7)
	v_lshlrev_b32_e32 v30, 16, v160
	v_and_b32_e32 v31, 0xffff0000, v160
	v_lshlrev_b32_e32 v24, 16, v161
	v_and_b32_e32 v25, 0xffff0000, v161
	v_pk_mul_f32 v[28:29], v[28:29], v[30:31]
	v_pk_mul_f32 v[24:25], v[26:27], v[24:25]
	v_cvt_pk_bf16_f32 v26, v28, v29
	v_cvt_pk_bf16_f32 v27, v24, v25
	global_store_dwordx2 v[0:1], v[26:27], off offset:288
	ds_read2_b64 v[24:27], v127 offset0:40 offset1:44
	s_waitcnt lgkmcnt(0)
	v_lshlrev_b32_e32 v30, 16, v24
	v_and_b32_e32 v31, 0xffff0000, v24
	v_lshlrev_b32_e32 v24, 16, v25
	v_and_b32_e32 v25, 0xffff0000, v25
	v_pk_fma_f32 v[30:31], v[100:101], v[30:31], v[32:33]
	v_pk_fma_f32 v[24:25], v[100:101], v[24:25], v[34:35]
	s_waitcnt vmcnt(7)
	v_lshlrev_b32_e32 v32, 16, v162
	v_and_b32_e32 v33, 0xffff0000, v162
	v_lshlrev_b32_e32 v28, 16, v163
	v_and_b32_e32 v29, 0xffff0000, v163
	v_pk_mul_f32 v[30:31], v[30:31], v[32:33]
	v_pk_mul_f32 v[24:25], v[24:25], v[28:29]
	v_cvt_pk_bf16_f32 v28, v30, v31
	v_cvt_pk_bf16_f32 v29, v24, v25
	global_store_dwordx2 v[0:1], v[28:29], off offset:320
	v_lshlrev_b32_e32 v28, 16, v26
	v_and_b32_e32 v29, 0xffff0000, v26
	v_lshlrev_b32_e32 v26, 16, v27
	v_and_b32_e32 v27, 0xffff0000, v27
	v_pk_fma_f32 v[20:21], v[100:101], v[28:29], v[20:21]
	v_pk_fma_f32 v[22:23], v[100:101], v[26:27], v[22:23]
	s_waitcnt vmcnt(7)
	v_lshlrev_b32_e32 v26, 16, v164
	v_and_b32_e32 v27, 0xffff0000, v164
	v_lshlrev_b32_e32 v24, 16, v165
	v_and_b32_e32 v25, 0xffff0000, v165
	v_pk_mul_f32 v[20:21], v[20:21], v[26:27]
	v_pk_mul_f32 v[22:23], v[22:23], v[24:25]
	v_cvt_pk_bf16_f32 v20, v20, v21
	v_cvt_pk_bf16_f32 v21, v22, v23
	global_store_dwordx2 v[0:1], v[20:21], off offset:352
	ds_read2_b64 v[20:23], v127 offset0:48 offset1:52
	s_waitcnt lgkmcnt(0)
	v_lshlrev_b32_e32 v26, 16, v20
	v_and_b32_e32 v27, 0xffff0000, v20
	v_lshlrev_b32_e32 v20, 16, v21
	v_and_b32_e32 v21, 0xffff0000, v21
	v_pk_fma_f32 v[12:13], v[100:101], v[26:27], v[12:13]
	v_pk_fma_f32 v[14:15], v[100:101], v[20:21], v[14:15]
	s_waitcnt vmcnt(7)
	v_lshlrev_b32_e32 v20, 16, v166
	v_and_b32_e32 v21, 0xffff0000, v166
	v_lshlrev_b32_e32 v24, 16, v167
	v_and_b32_e32 v25, 0xffff0000, v167
	v_pk_mul_f32 v[12:13], v[12:13], v[20:21]
	v_pk_mul_f32 v[14:15], v[14:15], v[24:25]
	v_cvt_pk_bf16_f32 v12, v12, v13
	v_cvt_pk_bf16_f32 v13, v14, v15
	global_store_dwordx2 v[0:1], v[12:13], off offset:384
	v_lshlrev_b32_e32 v14, 16, v22
	v_and_b32_e32 v15, 0xffff0000, v22
	v_lshlrev_b32_e32 v20, 16, v23
	v_and_b32_e32 v21, 0xffff0000, v23
	v_pk_fma_f32 v[14:15], v[100:101], v[14:15], v[16:17]
	v_pk_fma_f32 v[16:17], v[100:101], v[20:21], v[18:19]
	s_waitcnt vmcnt(7)
	v_lshlrev_b32_e32 v18, 16, v168
	v_and_b32_e32 v19, 0xffff0000, v168
	v_lshlrev_b32_e32 v12, 16, v169
	v_and_b32_e32 v13, 0xffff0000, v169
	v_pk_mul_f32 v[14:15], v[14:15], v[18:19]
	v_pk_mul_f32 v[12:13], v[16:17], v[12:13]
	v_cvt_pk_bf16_f32 v14, v14, v15
	v_cvt_pk_bf16_f32 v15, v12, v13
	global_store_dwordx2 v[0:1], v[14:15], off offset:416
	ds_read2_b64 v[12:15], v127 offset0:56 offset1:60
	s_waitcnt lgkmcnt(0)
	v_lshlrev_b32_e32 v18, 16, v12
	v_and_b32_e32 v19, 0xffff0000, v12
	v_lshlrev_b32_e32 v12, 16, v13
	v_and_b32_e32 v13, 0xffff0000, v13
	v_pk_fma_f32 v[8:9], v[100:101], v[18:19], v[8:9]
	v_pk_fma_f32 v[10:11], v[100:101], v[12:13], v[10:11]
	s_waitcnt vmcnt(7)
	v_lshlrev_b32_e32 v12, 16, v170
	v_and_b32_e32 v13, 0xffff0000, v170
	v_lshlrev_b32_e32 v16, 16, v171
	v_and_b32_e32 v17, 0xffff0000, v171
	v_pk_mul_f32 v[8:9], v[8:9], v[12:13]
	v_pk_mul_f32 v[10:11], v[10:11], v[16:17]
	v_cvt_pk_bf16_f32 v8, v8, v9
	v_cvt_pk_bf16_f32 v9, v10, v11
	global_store_dwordx2 v[0:1], v[8:9], off offset:448
	s_load_dword s0, s[0:1], 0x0
	v_lshlrev_b32_e32 v8, 16, v14
	v_and_b32_e32 v9, 0xffff0000, v14
	v_lshlrev_b32_e32 v10, 16, v15
	v_and_b32_e32 v11, 0xffff0000, v15
	v_pk_fma_f32 v[4:5], v[100:101], v[8:9], v[4:5]
	v_pk_fma_f32 v[6:7], v[100:101], v[10:11], v[6:7]
	s_waitcnt lgkmcnt(0)
	s_add_i32 s6, s6, s0
	s_cmpk_gt_i32 s6, 0x1ff
	s_waitcnt vmcnt(7)
	v_lshlrev_b32_e32 v8, 16, v172
	v_and_b32_e32 v9, 0xffff0000, v172
	v_lshlrev_b32_e32 v2, 16, v173
	v_and_b32_e32 v3, 0xffff0000, v173
	v_pk_mul_f32 v[4:5], v[4:5], v[8:9]
	v_pk_mul_f32 v[2:3], v[6:7], v[2:3]
	v_cvt_pk_bf16_f32 v4, v4, v5
	v_cvt_pk_bf16_f32 v5, v2, v3
	global_store_dwordx2 v[0:1], v[4:5], off offset:480
	s_cbranch_scc1 .LBB0_816

; __device__ __forceinline__ unsigned cvt_pk_bf16(float lo, float hi) { const f32x2_t v = {lo, hi}; const bf16x2_t b = __builtin_convertvector(v, bf16x2_t); return __builtin_bit_cast(unsigned, b); }
; __device__ __forceinline__ float lo_bf(unsigned w) { return __uint_as_float(w << 16); }
; __device__ __forceinline__ float hi_bf(unsigned w) { return __uint_as_float(w & 0xffff0000u); }
; __device__ void hyena_phase(unsigned char* smem, const Params& p, int l, int order) {
;     ...
;             for (int mi = 0; mi < 8; ++mi) { const int t = tb + mi * 16 + 4 * g4;
;                 const u32x2 gw = *(const u32x2*)(gin + (size_t)r16 * SEQ + t); const u32x2 zw = *(const u32x2*)(zs + r16 * ZS + t);
;                 const float gv[4] = {lo_bf(gw.x), hi_bf(gw.x), lo_bf(gw.y), hi_bf(gw.y)}; const float zv[4] = {lo_bf(zw.x), hi_bf(zw.x), lo_bf(zw.y), hi_bf(zw.y)};
;                 float o[4];
; #pragma unroll
;                 for (int i = 0; i < 4; ++i) o[i] = gv[i] * (acc[mi][i] + sk * zv[i]);
;                 u32x2 wv; wv.x = cvt_pk_bf16(o[0], o[1]); wv.y = cvt_pk_bf16(o[2], o[3]); *(u32x2*)(dst + (size_t)r16 * SEQ + t) = wv; }
.LBB0_236:
	v_lshl_add_u64 v[104:105], v[92:93], 0, s[12:13]
	v_lshl_add_u64 v[24:25], v[104:105], 0, v[96:97]
	global_load_dwordx2 v[142:143], v[24:25], off
	global_load_dwordx2 v[144:145], v[24:25], off offset:32
	global_load_dwordx2 v[146:147], v[24:25], off offset:64
	global_load_dwordx2 v[148:149], v[24:25], off offset:96
	global_load_dwordx2 v[150:151], v[24:25], off offset:128
	global_load_dwordx2 v[152:153], v[24:25], off offset:160
	global_load_dwordx2 v[154:155], v[24:25], off offset:192
	global_load_dwordx2 v[156:157], v[24:25], off offset:224
	ds_read2_b64 v[26:29], v127 offset1:4
	v_mov_b32_e32 v101, v100
	v_lshl_add_u64 v[102:103], v[94:95], 0, s[12:13]
	v_lshl_add_u64 v[68:69], v[102:103], 0, v[96:97]
	ds_read2_b64 v[70:73], v127 offset0:24 offset1:28
	s_waitcnt lgkmcnt(1)
	v_lshlrev_b32_e32 v32, 16, v26
	v_and_b32_e32 v33, 0xffff0000, v26
	v_lshlrev_b32_e32 v26, 16, v27
	v_and_b32_e32 v27, 0xffff0000, v27
	v_pk_fma_f32 v[32:33], v[100:101], v[32:33], v[60:61] op_sel_hi:[0,1,1]
	v_pk_fma_f32 v[26:27], v[100:101], v[26:27], v[62:63] op_sel_hi:[0,1,1]
	s_waitcnt lgkmcnt(0)
	v_lshlrev_b32_e32 v74, 16, v72
	v_and_b32_e32 v75, 0xffff0000, v72
	v_lshlrev_b32_e32 v72, 16, v73
	v_and_b32_e32 v73, 0xffff0000, v73
	v_pk_fma_f32 v[0:1], v[100:101], v[74:75], v[0:1] op_sel_hi:[0,1,1]
	v_pk_fma_f32 v[2:3], v[100:101], v[72:73], v[2:3] op_sel_hi:[0,1,1]
	s_mov_b32 s0, 0
	s_waitcnt vmcnt(7)
	v_lshlrev_b32_e32 v34, 16, v142
	v_and_b32_e32 v35, 0xffff0000, v142
	v_lshlrev_b32_e32 v30, 16, v143
	v_and_b32_e32 v31, 0xffff0000, v143
	v_pk_mul_f32 v[32:33], v[32:33], v[34:35]
	v_pk_mul_f32 v[26:27], v[26:27], v[30:31]
	v_cvt_pk_bf16_f32 v30, v32, v33
	v_cvt_pk_bf16_f32 v31, v26, v27
	global_store_dwordx2 v[68:69], v[30:31], off
	v_lshlrev_b32_e32 v30, 16, v28
	v_and_b32_e32 v31, 0xffff0000, v28
	v_lshlrev_b32_e32 v28, 16, v29
	v_and_b32_e32 v29, 0xffff0000, v29
	v_pk_fma_f32 v[30:31], v[100:101], v[30:31], v[48:49] op_sel_hi:[0,1,1]
	v_pk_fma_f32 v[28:29], v[100:101], v[28:29], v[50:51] op_sel_hi:[0,1,1]
	s_waitcnt vmcnt(7)
	v_lshlrev_b32_e32 v32, 16, v144
	v_and_b32_e32 v33, 0xffff0000, v144
	v_lshlrev_b32_e32 v26, 16, v145
	v_and_b32_e32 v27, 0xffff0000, v145
	v_pk_mul_f32 v[30:31], v[30:31], v[32:33]
	v_pk_mul_f32 v[26:27], v[28:29], v[26:27]
	v_cvt_pk_bf16_f32 v28, v30, v31
	v_cvt_pk_bf16_f32 v29, v26, v27
	global_store_dwordx2 v[68:69], v[28:29], off offset:32
	ds_read2_b64 v[26:29], v127 offset0:8 offset1:12
	s_waitcnt lgkmcnt(0)
	v_lshlrev_b32_e32 v32, 16, v26
	v_and_b32_e32 v33, 0xffff0000, v26
	v_lshlrev_b32_e32 v26, 16, v27
	v_and_b32_e32 v27, 0xffff0000, v27
	v_pk_fma_f32 v[20:21], v[100:101], v[32:33], v[20:21] op_sel_hi:[0,1,1]
	v_pk_fma_f32 v[22:23], v[100:101], v[26:27], v[22:23] op_sel_hi:[0,1,1]
	s_waitcnt vmcnt(7)
	v_lshlrev_b32_e32 v26, 16, v146
	v_and_b32_e32 v27, 0xffff0000, v146
	v_lshlrev_b32_e32 v30, 16, v147
	v_and_b32_e32 v31, 0xffff0000, v147
	v_pk_mul_f32 v[20:21], v[20:21], v[26:27]
	v_pk_mul_f32 v[22:23], v[22:23], v[30:31]
	v_cvt_pk_bf16_f32 v20, v20, v21
	v_cvt_pk_bf16_f32 v21, v22, v23
	global_store_dwordx2 v[68:69], v[20:21], off offset:64
	v_lshlrev_b32_e32 v22, 16, v28
	v_and_b32_e32 v23, 0xffff0000, v28
	v_lshlrev_b32_e32 v26, 16, v29
	v_and_b32_e32 v27, 0xffff0000, v29
	v_pk_fma_f32 v[16:17], v[100:101], v[22:23], v[16:17] op_sel_hi:[0,1,1]
	v_pk_fma_f32 v[18:19], v[100:101], v[26:27], v[18:19] op_sel_hi:[0,1,1]
	s_waitcnt vmcnt(7)
; __device__ __forceinline__ unsigned cvt_pk_bf16(float lo, float hi) { const f32x2_t v = {lo, hi}; const bf16x2_t b = __builtin_convertvector(v, bf16x2_t); return __builtin_bit_cast(unsigned, b); }
; __device__ __forceinline__ float lo_bf(unsigned w) { return __uint_as_float(w << 16); }
; __device__ __forceinline__ float hi_bf(unsigned w) { return __uint_as_float(w & 0xffff0000u); }
; __device__ void hyena_phase(unsigned char* smem, const Params& p, int l, int order) {
;     ...
;             const int tb = w * 256 + mg * 128;
;             f32x4 acc[8];
; #pragma unroll
;             for (int mi = 0; mi < 8; ++mi) acc[mi] = (f32x4){0.f, 0.f, 0.f, 0.f};
;             const bf16_t* fg = fbase - tb;
;             bf16x8 W[8];
; #pragma unroll
;             for (int i = 0; i < 8; ++i) W[i] = *(const bf16x8*)(fg - 16 * i);
;     ...
;             for (int mi = 0; mi < 8; ++mi) { const int t = tb + mi * 16 + 4 * g4;
;                 const u32x2 gw = *(const u32x2*)(gin + (size_t)r16 * SEQ + t); const u32x2 zw = *(const u32x2*)(zs + r16 * ZS + t);
;                 const float gv[4] = {lo_bf(gw.x), hi_bf(gw.x), lo_bf(gw.y), hi_bf(gw.y)}; const float zv[4] = {lo_bf(zw.x), hi_bf(zw.x), lo_bf(zw.y), hi_bf(zw.y)};
;                 float o[4];
; #pragma unroll
;                 for (int i = 0; i < 4; ++i) o[i] = gv[i] * (acc[mi][i] + sk * zv[i]);
;                 u32x2 wv; wv.x = cvt_pk_bf16(o[0], o[1]); wv.y = cvt_pk_bf16(o[2], o[3]); *(u32x2*)(dst + (size_t)r16 * SEQ + t) = wv; }
	v_lshlrev_b32_e32 v22, 16, v148
	v_and_b32_e32 v23, 0xffff0000, v148
	v_lshlrev_b32_e32 v20, 16, v149
	v_and_b32_e32 v21, 0xffff0000, v149
	v_pk_mul_f32 v[16:17], v[16:17], v[22:23]
	v_pk_mul_f32 v[18:19], v[18:19], v[20:21]
	v_cvt_pk_bf16_f32 v16, v16, v17
	v_cvt_pk_bf16_f32 v17, v18, v19
	global_store_dwordx2 v[68:69], v[16:17], off offset:96
	ds_read2_b64 v[16:19], v127 offset0:16 offset1:20
	s_waitcnt lgkmcnt(0)
	v_lshlrev_b32_e32 v22, 16, v16
	v_and_b32_e32 v23, 0xffff0000, v16
	v_lshlrev_b32_e32 v16, 16, v17
	v_and_b32_e32 v17, 0xffff0000, v17
	v_pk_fma_f32 v[8:9], v[100:101], v[22:23], v[8:9] op_sel_hi:[0,1,1]
	v_pk_fma_f32 v[10:11], v[100:101], v[16:17], v[10:11] op_sel_hi:[0,1,1]
	s_waitcnt vmcnt(7)
	v_lshlrev_b32_e32 v16, 16, v150
	v_and_b32_e32 v17, 0xffff0000, v150
	v_lshlrev_b32_e32 v20, 16, v151
	v_and_b32_e32 v21, 0xffff0000, v151
	v_pk_mul_f32 v[8:9], v[8:9], v[16:17]
	v_pk_mul_f32 v[10:11], v[10:11], v[20:21]
	v_cvt_pk_bf16_f32 v8, v8, v9
	v_cvt_pk_bf16_f32 v9, v10, v11
	global_store_dwordx2 v[68:69], v[8:9], off offset:128
	v_lshlrev_b32_e32 v10, 16, v18
	v_and_b32_e32 v11, 0xffff0000, v18
	v_lshlrev_b32_e32 v16, 16, v19
	v_and_b32_e32 v17, 0xffff0000, v19
	v_pk_fma_f32 v[10:11], v[100:101], v[10:11], v[12:13] op_sel_hi:[0,1,1]
	v_pk_fma_f32 v[12:13], v[100:101], v[16:17], v[14:15] op_sel_hi:[0,1,1]
	s_waitcnt vmcnt(7)
	v_lshlrev_b32_e32 v14, 16, v152
	v_and_b32_e32 v15, 0xffff0000, v152
	v_lshlrev_b32_e32 v8, 16, v153
	v_and_b32_e32 v9, 0xffff0000, v153
	v_pk_mul_f32 v[10:11], v[10:11], v[14:15]
	v_pk_mul_f32 v[8:9], v[12:13], v[8:9]
	v_cvt_pk_bf16_f32 v10, v10, v11
	v_cvt_pk_bf16_f32 v11, v8, v9
	global_store_dwordx2 v[68:69], v[10:11], off offset:160
	v_lshlrev_b32_e32 v10, 16, v70
	v_and_b32_e32 v11, 0xffff0000, v70
	v_lshlrev_b32_e32 v12, 16, v71
	v_and_b32_e32 v13, 0xffff0000, v71
	v_pk_fma_f32 v[4:5], v[100:101], v[10:11], v[4:5] op_sel_hi:[0,1,1]
	v_pk_fma_f32 v[6:7], v[100:101], v[12:13], v[6:7] op_sel_hi:[0,1,1]
	s_waitcnt vmcnt(7)
	v_lshlrev_b32_e32 v10, 16, v154
	v_and_b32_e32 v11, 0xffff0000, v154
	v_lshlrev_b32_e32 v8, 16, v155
	v_and_b32_e32 v9, 0xffff0000, v155
	v_pk_mul_f32 v[4:5], v[4:5], v[10:11]
	v_pk_mul_f32 v[6:7], v[6:7], v[8:9]
	v_cvt_pk_bf16_f32 v4, v4, v5
	v_cvt_pk_bf16_f32 v5, v6, v7
	global_store_dwordx2 v[68:69], v[4:5], off offset:192
	ds_read_b128 v[48:51], v126 offset:3840
	ds_read_b128 v[44:47], v126 offset:3808
	ds_read_b128 v[56:59], v126 offset:3776
	ds_read_b128 v[60:63], v126 offset:3744
	ds_read_b128 v[36:39], v126 offset:3712
	ds_read_b128 v[40:43], v126 offset:3680
	ds_read_b128 v[28:31], v126 offset:3616
	ds_read_b128 v[24:27], v126 offset:3648
	v_mov_b32_e32 v4, 0
	v_mov_b32_e32 v5, v4
	v_mov_b32_e32 v6, v4
	v_mov_b32_e32 v7, v4
	v_mov_b32_e32 v8, v4
	v_mov_b32_e32 v9, v4
	v_mov_b32_e32 v10, v4
	v_mov_b32_e32 v11, v4
	v_mov_b32_e32 v16, v4
	v_mov_b32_e32 v17, v4
	v_mov_b32_e32 v18, v4
	v_mov_b32_e32 v19, v4
	v_mov_b32_e32 v12, v4
	v_mov_b32_e32 v13, v4
	v_mov_b32_e32 v14, v4
	v_mov_b32_e32 v15, v4
	v_mov_b32_e32 v20, v4
	v_mov_b32_e32 v21, v4
	v_mov_b32_e32 v22, v4
	v_mov_b32_e32 v23, v4
	v_mov_b32_e32 v32, v4
	v_mov_b32_e32 v33, v4
	v_mov_b32_e32 v34, v4
	v_mov_b32_e32 v35, v4
	v_mov_b32_e32 v52, v4
	v_mov_b32_e32 v53, v4
	v_mov_b32_e32 v54, v4
	v_mov_b32_e32 v55, v4
	v_mov_b32_e32 v64, v4
	v_mov_b32_e32 v65, v4
	v_mov_b32_e32 v66, v4
	v_mov_b32_e32 v67, v4
	s_waitcnt vmcnt(7)
	v_lshlrev_b32_e32 v72, 16, v156
	v_and_b32_e32 v73, 0xffff0000, v156
	v_lshlrev_b32_e32 v70, 16, v157
	v_and_b32_e32 v71, 0xffff0000, v157
	v_pk_mul_f32 v[0:1], v[0:1], v[72:73]
	v_pk_mul_f32 v[2:3], v[2:3], v[70:71]
	v_cvt_pk_bf16_f32 v0, v0, v1
	v_cvt_pk_bf16_f32 v1, v2, v3
	global_store_dwordx2 v[68:69], v[0:1], off offset:224
	s_branch .LBB0_238
